# peel + SwiGLU GEMM: first two load-segment waits of each unit relaxed to vmcnt(16) so the 8 epilogue stores need not retire before the first MFMA blocks
# speedup vs baseline: 1.0083x; 1.0061x over previous
; #define PG8_STAGE(bufoff, gbase, voff) do { _Pragma("unroll") for (int _i = 0; _i < 2; ++_i) \
;         __builtin_amdgcn_global_load_lds((const unsigned*)((const char*)(gbase) + (voff)[_i]), (PG8_LAS unsigned*)(lds + (bufoff) + ldsw + _i * 8192), 16, 0, 0); } while (0)
; #define PG8_WAIT_V(n) asm volatile("s_waitcnt vmcnt(" #n ")" ::: "memory")
; #define PG8_BAR __builtin_amdgcn_s_barrier()
; template <class Epi, class Sched, bool ALIGN_EPI = false, bool SP2 = false>
; __device__ __forceinline__ void gemm_phase(PG8_LAS unsigned char* lds, const Gemm g, const Sched& S, const Epi& E) {
;     ...
;     const int wid = __builtin_amdgcn_readfirstlane(tid >> 6), lane = tid & 63, wr = wid >> 2, wc = wid & 3, fr = lane & 15, fq = lane >> 4;
;     const int K = g.K, nt = K / BK;
;     unsigned voffA[2], voffB[2];
; #pragma unroll
;     for (int i = 0; i < 2; ++i) { int R, C; stage_rc(tid * 16 + i * 8192, R, C); const int Rb = Epi::PERM ? ((R & ~31) + perm32(R & 31)) : R;
;         voffA[i] = g.tiledA ? (unsigned)((C >> 5) * 8192 + R * 64 + (C & 31) * 2) : (unsigned)(R * K + C) * 2u; voffB[i] = (unsigned)(Rb * K + C) * 2u; }
;     const size_t kstep = (size_t)(BK * 2);
;     const size_t kstepA = g.tiledA ? (size_t)16384 : kstep;
;     const size_t hstep = (size_t)HALF * K * 2;
;     const size_t tstep = 2 * hstep;
;     const unsigned ldsw = (unsigned)wid * 1024u;
;     const int aoff = lds_byte(wr * 64 + fr, fq * 8), boff = lds_byte(wc * 32 + fr, fq * 8);
;     ...
;         PG8_STAGE(PG8_SB(0, 0), cB, voffB); PG8_STAGE(PG8_SB(0, 1), cB + hstep, voffB); PG8_STAGE(PG8_SA(0, 0), cA, voffA); PG8_STAGE(PG8_SA(0, 1), cA + hstep, voffA);
;         if (wr == 1) PG8_BAR;
;         PG8_WAIT_V(2); PG8_BAR;
;         PG8_STAGE(PG8_SB(1, 0), cB + kstep, voffB); PG8_STAGE(PG8_SA(1, 0), cA + kstepA, voffA); PG8_STAGE(PG8_SB(1, 1), cB + hstep + kstep, voffB);
;         PG8_WAIT_V(6); PG8_BAR;
.LBB0_403:
	s_and_b32 s34, s7, 3
	s_add_i32 m0, s45, 0x18000
	v_lshl_add_u64 v[2:3], v[2:3], 0, s[38:39]
	s_lshl_b32 s7, s5, 13
	s_lshl_b32 s10, s34, 12
	s_waitcnt vmcnt(2)
	s_barrier
	global_load_lds_dwordx4 v[2:3], off
	s_add_i32 m0, s45, 0x1a000
	s_add_u32 s8, s22, 0x4000
	v_mov_b32_e32 v135, v1
	v_lshl_add_u64 v[2:3], v[4:5], 0, s[38:39]
	s_addc_u32 s9, s23, 0
	s_add_i32 s49, s45, 0x8000
	v_mov_b32_e32 v133, v1
	global_load_lds_dwordx4 v[2:3], off
	v_lshl_add_u64 v[2:3], s[8:9], 0, v[134:135]
	s_mov_b32 m0, s49
	s_add_i32 s50, s45, 0xa000
	global_load_lds_dwordx4 v[2:3], off
	v_lshl_add_u64 v[2:3], s[8:9], 0, v[132:133]
	s_add_u32 s8, s24, 0x40080
	s_mov_b32 m0, s50
	s_addc_u32 s9, s25, 0
	global_load_lds_dwordx4 v[2:3], off
	s_add_i32 m0, s45, 0x1c000
	v_lshl_add_u64 v[2:3], s[8:9], 0, v[0:1]
	global_load_lds_dwordx4 v[2:3], off
	v_lshl_add_u64 v[2:3], s[8:9], 0, v[130:131]
	s_add_i32 m0, s45, 0x1e000
	s_cmpk_lt_u32 s6, 0x100
	global_load_lds_dwordx4 v[2:3], off
	v_and_b32_e32 v3, 15, v6
	v_and_b32_e32 v2, 48, v6
	v_lshlrev_b32_e32 v6, 2, v3
	v_lshl_or_b32 v4, v3, 6, v2
	v_and_b32_e32 v5, 32, v6
	v_lshlrev_b32_e32 v3, 5, v3
	v_bitop3_b32 v15, v4, s7, v5 bitop3:0xde
	v_bitop3_b32 v142, v4, s10, v5 bitop3:0xde
	v_lshl_or_b32 v4, s5, 11, v3
	v_ashrrev_i32_e32 v5, 31, v4
	v_lshl_add_u64 v[4:5], v[4:5], 1, s[56:57]
	v_mov_b32_e32 v3, v1
	s_sext_i32_i16 s21, s4
	s_cselect_b64 s[6:7], -1, 0
	s_lshl_b32 s4, s5, 8
	v_lshl_add_u64 v[136:137], v[4:5], 0, v[2:3]
	v_lshlrev_b32_e32 v2, 9, v7
	s_add_i32 s4, s4, 0
	v_and_b32_e32 v2, 0xfffffc00, v2
	s_add_i32 s4, s4, 0x20000
	v_add_u32_e32 v2, v9, v2
	v_add_u32_e32 v143, s4, v6
	v_add3_u32 v2, v2, v8, v10
	s_mov_b64 s[4:5], 0x44000
	v_lshl_add_u64 v[138:139], v[2:3], 0, s[4:5]
	v_lshlrev_b32_e32 v2, 9, v11
	v_and_b32_e32 v2, 0xfffffc00, v2
	s_waitcnt vmcnt(6)
	v_add_u32_e32 v2, v13, v2
	v_add3_u32 v2, v2, v12, v14
	v_lshl_add_u64 v[140:141], v[2:3], 0, s[4:5]
	s_mov_b32 s52, 0
	v_add_u32_e32 v144, 0, v15
	s_waitcnt vmcnt(0)
	s_barrier
	s_branch .LBB0_406

; #define PG8_STAGE(bufoff, gbase, voff) do { _Pragma("unroll") for (int _i = 0; _i < 2; ++_i) \
;         __builtin_amdgcn_global_load_lds((const unsigned*)((const char*)(gbase) + (voff)[_i]), (PG8_LAS unsigned*)(lds + (bufoff) + ldsw + _i * 8192), 16, 0, 0); } while (0)
; #define PG8_LDA(dst, b, h) do { _Pragma("unroll") for (int m = 0; m < 4; ++m) _Pragma("unroll") for (int k = 0; k < 2; ++k) dst[m][k] = *(const PG8_LAS bf16x8*)(lds + PG8_SA(b, h) + aoff + m * 2048 + k * 1024); } while (0)
; #define PG8_LDB(dst, b, h) do { _Pragma("unroll") for (int n = 0; n < 2; ++n) _Pragma("unroll") for (int k = 0; k < 2; ++k) dst[n][k] = *(const PG8_LAS bf16x8*)(lds + PG8_SB(b, h) + boff + n * 2048 + k * 1024); } while (0)
; #define PG8_WAIT_V(n) asm volatile("s_waitcnt vmcnt(" #n ")" ::: "memory")
; #define PG8_WAIT_L(n) asm volatile("s_waitcnt lgkmcnt(" #n ")" ::: "memory")
; #define PG8_BAR __builtin_amdgcn_s_barrier()
; #define PG8_SCHED __builtin_amdgcn_sched_barrier(0)
; template <class Epi, class Sched, bool ALIGN_EPI = false, bool SP2 = false>
; __device__ __forceinline__ void gemm_phase(PG8_LAS unsigned char* lds, const Gemm g, const Sched& S, const Epi& E) {
;     ...
;         const char* nA = has_next ? (const char*)g.A + (size_t)nxt.pm * tstep : cA; const char* nB = has_next ? (const char*)g.Bt + (size_t)nxt.pn * tstep : cB;
;         for (int t = 0; t < nt; t += 2) {
;             const bool last = (t == nt - 2);
;             const char* a1 = cA + (size_t)(t + 1) * kstepA;
;             const char* a2 = last ? nA : cA + (size_t)(t + 2) * kstepA; const char* b2 = last ? nB : cB + (size_t)(t + 2) * kstep;
;             const char* a3 = a2 + kstepA; const char* b3 = b2 + kstep;
;             if (last && has_next) S.a_ready(nxt);
;             if constexpr (SP2) {
;             PG8_LDB(B0, 0, 0); PG8_LDB(B1, 0, 1); PG8_SCHED; PG8_LDA(At, 0, 0); PG8_STAGE(PG8_SA(1, 1), a1 + hstep, voffA);
;             PG8_WAIT_V(8); PG8_WAIT_L(0); PG8_BAR; PG8_MMA(0, 0, At, B0); PG8_MMA(0, 1, At, B1); PG8_BAR; PG8_SCHED;
;             PG8_LDA(At, 0, 1); PG8_STAGE(PG8_SB(0, 0), b2, voffB); PG8_STAGE(PG8_SB(0, 1), b2 + hstep, voffB); PG8_STAGE(PG8_SA(0, 0), a2, voffA);
;             PG8_WAIT_V(8); PG8_WAIT_L(0); PG8_BAR; PG8_MMA(1, 0, At, B0); PG8_MMA(1, 1, At, B1); PG8_BAR; PG8_SCHED;
.LBB0_408:
	s_ashr_i32 s11, s10, 31
	s_lshl_b64 s[12:13], s[10:11], 19
	s_add_u32 s12, s30, s12
	s_addc_u32 s13, s31, s13
	s_and_b64 s[18:19], s[4:5], exec
	s_cselect_b32 s11, s13, s23
	s_cselect_b32 s53, s12, s22
	s_ashr_i32 s9, s8, 31
	s_lshl_b64 s[18:19], s[8:9], 19
	s_add_u32 s18, s37, s18
	s_addc_u32 s19, s44, s19
	s_and_b64 s[26:27], s[4:5], exec
	s_cselect_b32 s9, s19, s25
	s_cselect_b32 s54, s18, s24
	s_add_u32 s55, s24, 0x100
	s_addc_u32 s56, s25, 0
	s_mov_b32 s57, -2
	s_add_u32 s24, s22, 0x8000
	s_addc_u32 s25, s23, 0
	s_cmp_eq_u32 s57, 12
	s_cselect_b32 s42, s53, s24
	s_cselect_b32 s43, s11, s25
	s_cselect_b32 s40, s54, s55
	s_cselect_b32 s41, s9, s56
	s_add_u32 s26, s42, 0x4000
	s_addc_u32 s27, s43, 0
	v_add_u32_e32 v145, s76, v142
	s_add_i32 s58, 0, 0x14000
	ds_read_b128 v[146:149], v145
	ds_read_b128 v[150:153], v145 offset:1024
	ds_read_b128 v[160:163], v145 offset:2048
	ds_read_b128 v[164:167], v145 offset:3072
	v_add_u32_e32 v145, s58, v142
	ds_read_b128 v[168:171], v145
	ds_read_b128 v[172:175], v145 offset:1024
	ds_read_b128 v[176:179], v145 offset:2048
	ds_read_b128 v[180:183], v145 offset:3072
	v_lshl_add_u64 v[230:231], s[22:23], 0, v[140:141]
	s_add_i32 m0, s45, 0xc000
	ds_read_b128 v[184:187], v144
	ds_read_b128 v[188:191], v144 offset:1024
	ds_read_b128 v[206:209], v144 offset:2048
	ds_read_b128 v[210:213], v144 offset:3072
	ds_read_b128 v[214:217], v144 offset:4096
	ds_read_b128 v[218:221], v144 offset:5120
	ds_read_b128 v[222:225], v144 offset:6144
	ds_read_b128 v[226:229], v144 offset:7168
	global_load_lds_dwordx4 v[230:231], off
	v_lshl_add_u64 v[230:231], s[22:23], 0, v[138:139]
	s_add_i32 m0, s45, 0xe000
	s_nop 0
	global_load_lds_dwordx4 v[230:231], off
	s_waitcnt vmcnt(16)
	s_waitcnt lgkmcnt(0)
	s_barrier
	v_mfma_f32_16x16x32_bf16 v[126:129], v[146:149], v[184:187], 0
	v_mfma_f32_16x16x32_bf16 v[126:129], v[150:153], v[188:191], v[126:129]
	v_mfma_f32_16x16x32_bf16 v[118:121], v[164:167], v[188:191], 0
	v_mfma_f32_16x16x32_bf16 v[118:121], v[160:163], v[184:187], v[118:121]
	v_mfma_f32_16x16x32_bf16 v[102:105], v[160:163], v[206:209], 0
	v_mfma_f32_16x16x32_bf16 v[102:105], v[164:167], v[210:213], v[102:105]
	v_mfma_f32_16x16x32_bf16 v[110:113], v[150:153], v[210:213], 0
	v_mfma_f32_16x16x32_bf16 v[110:113], v[146:149], v[206:209], v[110:113]
	v_mfma_f32_16x16x32_bf16 v[94:97], v[146:149], v[214:217], 0
	v_mfma_f32_16x16x32_bf16 v[94:97], v[150:153], v[218:221], v[94:97]
	v_mfma_f32_16x16x32_bf16 v[86:89], v[164:167], v[218:221], 0
	v_mfma_f32_16x16x32_bf16 v[86:89], v[160:163], v[214:217], v[86:89]
	v_mfma_f32_16x16x32_bf16 v[70:73], v[160:163], v[222:225], 0
	v_mfma_f32_16x16x32_bf16 v[70:73], v[164:167], v[226:229], v[70:73]
	v_mfma_f32_16x16x32_bf16 v[78:81], v[150:153], v[226:229], 0
	v_mfma_f32_16x16x32_bf16 v[78:81], v[146:149], v[222:225], v[78:81]
	v_mfma_f32_16x16x32_bf16 v[122:125], v[168:171], v[184:187], 0
	v_mfma_f32_16x16x32_bf16 v[122:125], v[172:175], v[188:191], v[122:125]
	v_mfma_f32_16x16x32_bf16 v[114:117], v[180:183], v[188:191], 0
	v_mfma_f32_16x16x32_bf16 v[114:117], v[176:179], v[184:187], v[114:117]
	v_mfma_f32_16x16x32_bf16 v[98:101], v[176:179], v[206:209], 0
	v_mfma_f32_16x16x32_bf16 v[98:101], v[180:183], v[210:213], v[98:101]
	v_mfma_f32_16x16x32_bf16 v[106:109], v[172:175], v[210:213], 0
	v_mfma_f32_16x16x32_bf16 v[106:109], v[168:171], v[206:209], v[106:109]
	v_mfma_f32_16x16x32_bf16 v[90:93], v[168:171], v[214:217], 0
	v_mfma_f32_16x16x32_bf16 v[90:93], v[172:175], v[218:221], v[90:93]
	v_mfma_f32_16x16x32_bf16 v[82:85], v[180:183], v[218:221], 0
	v_mfma_f32_16x16x32_bf16 v[82:85], v[176:179], v[214:217], v[82:85]
	v_mfma_f32_16x16x32_bf16 v[66:69], v[176:179], v[222:225], 0
	v_mfma_f32_16x16x32_bf16 v[66:69], v[180:183], v[226:229], v[66:69]
	v_mfma_f32_16x16x32_bf16 v[74:77], v[172:175], v[226:229], 0
	v_mfma_f32_16x16x32_bf16 v[74:77], v[168:171], v[222:225], v[74:77]
	s_barrier
	s_add_i32 s22, s76, s29
	v_lshl_add_u64 v[230:231], s[40:41], 0, v[0:1]
	s_mov_b32 m0, s22
	ds_read_b128 v[184:187], v144 offset:16384
	ds_read_b128 v[188:191], v144 offset:17408
	ds_read_b128 v[206:209], v144 offset:18432
	ds_read_b128 v[210:213], v144 offset:19456
	ds_read_b128 v[214:217], v144 offset:20480
	ds_read_b128 v[218:221], v144 offset:21504
	ds_read_b128 v[222:225], v144 offset:22528
	ds_read_b128 v[226:229], v144 offset:23552
	global_load_lds_dwordx4 v[230:231], off
	s_add_i32 m0, s22, 0x2000
	s_add_u32 s22, s40, 0x40000
	v_lshl_add_u64 v[232:233], s[40:41], 0, v[130:131]
	s_addc_u32 s23, s41, 0
	s_add_i32 s58, s58, s29
	global_load_lds_dwordx4 v[232:233], off
	v_lshl_add_u64 v[234:235], s[22:23], 0, v[0:1]
	s_mov_b32 m0, s58
	s_nop 0
	global_load_lds_dwordx4 v[234:235], off
	v_lshl_add_u64 v[234:235], s[22:23], 0, v[130:131]
	s_add_i32 m0, s58, 0x2000
	s_nop 0
	global_load_lds_dwordx4 v[234:235], off
	v_lshl_add_u64 v[234:235], s[42:43], 0, v[134:135]
	s_mov_b32 m0, s45
	s_nop 0
	global_load_lds_dwordx4 v[234:235], off
	v_lshl_add_u64 v[234:235], s[42:43], 0, v[132:133]
	s_mov_b32 m0, s46
	s_nop 0
	global_load_lds_dwordx4 v[234:235], off
	s_waitcnt vmcnt(16)
	s_waitcnt lgkmcnt(0)
	s_barrier
; #define PG8_STAGE(bufoff, gbase, voff) do { _Pragma("unroll") for (int _i = 0; _i < 2; ++_i) \
;         __builtin_amdgcn_global_load_lds((const unsigned*)((const char*)(gbase) + (voff)[_i]), (PG8_LAS unsigned*)(lds + (bufoff) + ldsw + _i * 8192), 16, 0, 0); } while (0)
; #define PG8_LDA(dst, b, h) do { _Pragma("unroll") for (int m = 0; m < 4; ++m) _Pragma("unroll") for (int k = 0; k < 2; ++k) dst[m][k] = *(const PG8_LAS bf16x8*)(lds + PG8_SA(b, h) + aoff + m * 2048 + k * 1024); } while (0)
; #define PG8_LDB(dst, b, h) do { _Pragma("unroll") for (int n = 0; n < 2; ++n) _Pragma("unroll") for (int k = 0; k < 2; ++k) dst[n][k] = *(const PG8_LAS bf16x8*)(lds + PG8_SB(b, h) + boff + n * 2048 + k * 1024); } while (0)
; #define PG8_MMA(ai, bj, At, Bt) do { __builtin_amdgcn_s_setprio(1); _Pragma("unroll") for (int m = 0; m < 4; ++m) _Pragma("unroll") for (int n = 0; n < 2; ++n) _Pragma("unroll") for (int k = 0; k < 2; ++k) \
;         acc[ai][bj][m][n] = __builtin_amdgcn_mfma_f32_16x16x32_bf16(Bt[n][k], At[m][k], acc[ai][bj][m][n], 0, 0, 0); __builtin_amdgcn_s_setprio(0); } while (0)
; #define PG8_WAIT_V(n) asm volatile("s_waitcnt vmcnt(" #n ")" ::: "memory")
; #define PG8_WAIT_L(n) asm volatile("s_waitcnt lgkmcnt(" #n ")" ::: "memory")
; #define PG8_BAR __builtin_amdgcn_s_barrier()
; #define PG8_SCHED __builtin_amdgcn_sched_barrier(0)
; template <class Epi, class Sched, bool ALIGN_EPI = false, bool SP2 = false>
; __device__ __forceinline__ void gemm_phase(PG8_LAS unsigned char* lds, const Gemm g, const Sched& S, const Epi& E) {
;     ...
;             PG8_WAIT_V(8); PG8_WAIT_L(0); PG8_BAR; PG8_MMA(1, 0, At, B0); PG8_MMA(1, 1, At, B1); PG8_BAR; PG8_SCHED;
;             PG8_LDB(B0, 1, 0); PG8_LDB(B1, 1, 1); PG8_SCHED; PG8_LDA(At, 1, 0); PG8_STAGE(PG8_SA(0, 1), a2 + hstep, voffA);
;             PG8_WAIT_V(8); PG8_WAIT_L(0); PG8_BAR; PG8_MMA(0, 0, At, B0); PG8_MMA(0, 1, At, B1); PG8_BAR; PG8_SCHED;
	v_mfma_f32_16x16x32_bf16 v[62:65], v[146:149], v[184:187], 0
	v_mfma_f32_16x16x32_bf16 v[62:65], v[150:153], v[188:191], v[62:65]
	v_mfma_f32_16x16x32_bf16 v[54:57], v[164:167], v[188:191], 0
	v_mfma_f32_16x16x32_bf16 v[54:57], v[160:163], v[184:187], v[54:57]
	v_mfma_f32_16x16x32_bf16 v[38:41], v[160:163], v[206:209], 0
	v_mfma_f32_16x16x32_bf16 v[38:41], v[164:167], v[210:213], v[38:41]
	v_mfma_f32_16x16x32_bf16 v[46:49], v[150:153], v[210:213], 0
	v_mfma_f32_16x16x32_bf16 v[46:49], v[146:149], v[206:209], v[46:49]
	v_mfma_f32_16x16x32_bf16 v[30:33], v[146:149], v[214:217], 0
	v_mfma_f32_16x16x32_bf16 v[30:33], v[150:153], v[218:221], v[30:33]
	v_mfma_f32_16x16x32_bf16 v[22:25], v[164:167], v[218:221], 0
	v_mfma_f32_16x16x32_bf16 v[22:25], v[160:163], v[214:217], v[22:25]
	v_mfma_f32_16x16x32_bf16 v[6:9], v[160:163], v[222:225], 0
	v_mfma_f32_16x16x32_bf16 v[6:9], v[164:167], v[226:229], v[6:9]
	v_mfma_f32_16x16x32_bf16 v[14:17], v[150:153], v[226:229], 0
	v_mfma_f32_16x16x32_bf16 v[14:17], v[146:149], v[222:225], v[14:17]
	v_mfma_f32_16x16x32_bf16 v[58:61], v[168:171], v[184:187], 0
	v_mfma_f32_16x16x32_bf16 v[58:61], v[172:175], v[188:191], v[58:61]
	v_mfma_f32_16x16x32_bf16 v[50:53], v[180:183], v[188:191], 0
	v_mfma_f32_16x16x32_bf16 v[50:53], v[176:179], v[184:187], v[50:53]
	v_mfma_f32_16x16x32_bf16 v[34:37], v[176:179], v[206:209], 0
	v_mfma_f32_16x16x32_bf16 v[34:37], v[180:183], v[210:213], v[34:37]
	v_mfma_f32_16x16x32_bf16 v[42:45], v[172:175], v[210:213], 0
	v_mfma_f32_16x16x32_bf16 v[42:45], v[168:171], v[206:209], v[42:45]
	v_mfma_f32_16x16x32_bf16 v[26:29], v[168:171], v[214:217], 0
	v_mfma_f32_16x16x32_bf16 v[26:29], v[172:175], v[218:221], v[26:29]
	v_mfma_f32_16x16x32_bf16 v[18:21], v[180:183], v[218:221], 0
	v_mfma_f32_16x16x32_bf16 v[18:21], v[176:179], v[214:217], v[18:21]
	v_mfma_f32_16x16x32_bf16 v[2:5], v[176:179], v[222:225], 0
	v_mfma_f32_16x16x32_bf16 v[2:5], v[180:183], v[226:229], v[2:5]
	v_mfma_f32_16x16x32_bf16 v[10:13], v[172:175], v[226:229], 0
	v_mfma_f32_16x16x32_bf16 v[10:13], v[168:171], v[222:225], v[10:13]
	s_barrier
	s_add_i32 s58, 0, 0x18000
	v_add_u32_e32 v145, s58, v142
	s_add_i32 s59, 0, 0x1c000
	ds_read_b128 v[146:149], v145
	ds_read_b128 v[150:153], v145 offset:1024
	ds_read_b128 v[160:163], v145 offset:2048
	ds_read_b128 v[164:167], v145 offset:3072
	v_add_u32_e32 v145, s59, v142
	ds_read_b128 v[168:171], v145
	ds_read_b128 v[172:175], v145 offset:1024
	ds_read_b128 v[176:179], v145 offset:2048
	ds_read_b128 v[180:183], v145 offset:3072
	s_add_u32 s22, s42, 0x40000
	s_addc_u32 s23, s43, 0
	s_mov_b32 m0, s47
	v_lshl_add_u64 v[234:235], s[22:23], 0, v[134:135]
	ds_read_b128 v[184:187], v144 offset:32768
	ds_read_b128 v[188:191], v144 offset:33792
	ds_read_b128 v[206:209], v144 offset:34816
	ds_read_b128 v[210:213], v144 offset:35840
	ds_read_b128 v[214:217], v144 offset:36864
	ds_read_b128 v[218:221], v144 offset:37888
	ds_read_b128 v[222:225], v144 offset:38912
	ds_read_b128 v[226:229], v144 offset:39936
	global_load_lds_dwordx4 v[234:235], off
	v_lshl_add_u64 v[234:235], s[22:23], 0, v[132:133]
	s_mov_b32 m0, s48
	s_nop 0
	global_load_lds_dwordx4 v[234:235], off
	s_waitcnt vmcnt(8)
	s_waitcnt lgkmcnt(0)
	s_barrier
	v_mfma_f32_16x16x32_bf16 v[126:129], v[146:149], v[184:187], v[126:129]
	v_mfma_f32_16x16x32_bf16 v[126:129], v[150:153], v[188:191], v[126:129]
	v_mfma_f32_16x16x32_bf16 v[118:121], v[164:167], v[188:191], v[118:121]
	v_mfma_f32_16x16x32_bf16 v[118:121], v[160:163], v[184:187], v[118:121]
	v_mfma_f32_16x16x32_bf16 v[102:105], v[160:163], v[206:209], v[102:105]
	v_mfma_f32_16x16x32_bf16 v[102:105], v[164:167], v[210:213], v[102:105]
	v_mfma_f32_16x16x32_bf16 v[110:113], v[150:153], v[210:213], v[110:113]
	v_mfma_f32_16x16x32_bf16 v[110:113], v[146:149], v[206:209], v[110:113]
	v_mfma_f32_16x16x32_bf16 v[94:97], v[146:149], v[214:217], v[94:97]
	v_mfma_f32_16x16x32_bf16 v[94:97], v[150:153], v[218:221], v[94:97]
	v_mfma_f32_16x16x32_bf16 v[86:89], v[164:167], v[218:221], v[86:89]
	v_mfma_f32_16x16x32_bf16 v[86:89], v[160:163], v[214:217], v[86:89]
	v_mfma_f32_16x16x32_bf16 v[70:73], v[160:163], v[222:225], v[70:73]
	v_mfma_f32_16x16x32_bf16 v[70:73], v[164:167], v[226:229], v[70:73]
	v_mfma_f32_16x16x32_bf16 v[78:81], v[150:153], v[226:229], v[78:81]
	v_mfma_f32_16x16x32_bf16 v[78:81], v[146:149], v[222:225], v[78:81]
	v_mfma_f32_16x16x32_bf16 v[122:125], v[168:171], v[184:187], v[122:125]
	v_mfma_f32_16x16x32_bf16 v[122:125], v[172:175], v[188:191], v[122:125]
	v_mfma_f32_16x16x32_bf16 v[114:117], v[180:183], v[188:191], v[114:117]
	v_mfma_f32_16x16x32_bf16 v[114:117], v[176:179], v[184:187], v[114:117]
	v_mfma_f32_16x16x32_bf16 v[98:101], v[176:179], v[206:209], v[98:101]
	v_mfma_f32_16x16x32_bf16 v[98:101], v[180:183], v[210:213], v[98:101]
	v_mfma_f32_16x16x32_bf16 v[106:109], v[172:175], v[210:213], v[106:109]
	v_mfma_f32_16x16x32_bf16 v[106:109], v[168:171], v[206:209], v[106:109]
	v_mfma_f32_16x16x32_bf16 v[90:93], v[168:171], v[214:217], v[90:93]
	v_mfma_f32_16x16x32_bf16 v[90:93], v[172:175], v[218:221], v[90:93]
	v_mfma_f32_16x16x32_bf16 v[82:85], v[180:183], v[218:221], v[82:85]
	v_mfma_f32_16x16x32_bf16 v[82:85], v[176:179], v[214:217], v[82:85]
	v_mfma_f32_16x16x32_bf16 v[66:69], v[176:179], v[222:225], v[66:69]
	v_mfma_f32_16x16x32_bf16 v[66:69], v[180:183], v[226:229], v[66:69]
	v_mfma_f32_16x16x32_bf16 v[74:77], v[172:175], v[226:229], v[74:77]
	v_mfma_f32_16x16x32_bf16 v[74:77], v[168:171], v[222:225], v[74:77]
	s_barrier
; #define PG8_STAGE(bufoff, gbase, voff) do { _Pragma("unroll") for (int _i = 0; _i < 2; ++_i) \
;         __builtin_amdgcn_global_load_lds((const unsigned*)((const char*)(gbase) + (voff)[_i]), (PG8_LAS unsigned*)(lds + (bufoff) + ldsw + _i * 8192), 16, 0, 0); } while (0)
; #define PG8_LDA(dst, b, h) do { _Pragma("unroll") for (int m = 0; m < 4; ++m) _Pragma("unroll") for (int k = 0; k < 2; ++k) dst[m][k] = *(const PG8_LAS bf16x8*)(lds + PG8_SA(b, h) + aoff + m * 2048 + k * 1024); } while (0)
; #define PG8_MMA(ai, bj, At, Bt) do { __builtin_amdgcn_s_setprio(1); _Pragma("unroll") for (int m = 0; m < 4; ++m) _Pragma("unroll") for (int n = 0; n < 2; ++n) _Pragma("unroll") for (int k = 0; k < 2; ++k) \
;         acc[ai][bj][m][n] = __builtin_amdgcn_mfma_f32_16x16x32_bf16(Bt[n][k], At[m][k], acc[ai][bj][m][n], 0, 0, 0); __builtin_amdgcn_s_setprio(0); } while (0)
; #define PG8_WAIT_V(n) asm volatile("s_waitcnt vmcnt(" #n ")" ::: "memory")
; #define PG8_WAIT_L(n) asm volatile("s_waitcnt lgkmcnt(" #n ")" ::: "memory")
; #define PG8_BAR __builtin_amdgcn_s_barrier()
; #define PG8_SCHED __builtin_amdgcn_sched_barrier(0)
; template <class Epi, class Sched, bool ALIGN_EPI = false, bool SP2 = false>
; __device__ __forceinline__ void gemm_phase(PG8_LAS unsigned char* lds, const Gemm g, const Sched& S, const Epi& E) {
;     ...
;             PG8_LDA(At, 1, 1); PG8_STAGE(PG8_SB(1, 0), b3, voffB); PG8_STAGE(PG8_SB(1, 1), b3 + hstep, voffB); PG8_STAGE(PG8_SA(1, 0), a3, voffA);
;             PG8_WAIT_V(8); PG8_WAIT_L(0); PG8_BAR; PG8_MMA(1, 0, At, B0); PG8_MMA(1, 1, At, B1); PG8_BAR; PG8_SCHED;
	s_add_i32 s22, s58, s29
	v_lshl_add_u64 v[230:231], v[230:231], 0, s[38:39]
	s_mov_b32 m0, s22
	ds_read_b128 v[184:187], v144 offset:49152
	ds_read_b128 v[188:191], v144 offset:50176
	ds_read_b128 v[206:209], v144 offset:51200
	ds_read_b128 v[210:213], v144 offset:52224
	ds_read_b128 v[214:217], v144 offset:53248
	ds_read_b128 v[218:221], v144 offset:54272
	ds_read_b128 v[222:225], v144 offset:55296
	ds_read_b128 v[226:229], v144 offset:56320
	global_load_lds_dwordx4 v[230:231], off
	s_add_i32 m0, s22, 0x2000
	s_add_u32 s22, s40, 0x40080
	v_lshl_add_u64 v[230:231], v[232:233], 0, s[38:39]
	s_addc_u32 s23, s41, 0
	s_add_i32 s40, s59, s29
	global_load_lds_dwordx4 v[230:231], off
	v_lshl_add_u64 v[230:231], s[22:23], 0, v[0:1]
	s_mov_b32 m0, s40
	s_nop 0
	global_load_lds_dwordx4 v[230:231], off
	v_lshl_add_u64 v[230:231], s[22:23], 0, v[130:131]
	s_add_i32 m0, s40, 0x2000
	s_nop 0
	global_load_lds_dwordx4 v[230:231], off
	v_lshl_add_u64 v[230:231], s[26:27], 0, v[134:135]
	s_mov_b32 m0, s49
	s_nop 0
	global_load_lds_dwordx4 v[230:231], off
	v_lshl_add_u64 v[230:231], s[26:27], 0, v[132:133]
	s_mov_b32 m0, s50
	s_nop 0
	global_load_lds_dwordx4 v[230:231], off
	s_waitcnt vmcnt(8)
	s_waitcnt lgkmcnt(0)
	s_barrier
	v_mfma_f32_16x16x32_bf16 v[62:65], v[146:149], v[184:187], v[62:65]
	v_mfma_f32_16x16x32_bf16 v[62:65], v[150:153], v[188:191], v[62:65]
	v_mfma_f32_16x16x32_bf16 v[54:57], v[164:167], v[188:191], v[54:57]
	v_mfma_f32_16x16x32_bf16 v[54:57], v[160:163], v[184:187], v[54:57]
	v_mfma_f32_16x16x32_bf16 v[38:41], v[160:163], v[206:209], v[38:41]
	v_mfma_f32_16x16x32_bf16 v[38:41], v[164:167], v[210:213], v[38:41]
	v_mfma_f32_16x16x32_bf16 v[46:49], v[150:153], v[210:213], v[46:49]
	v_mfma_f32_16x16x32_bf16 v[46:49], v[146:149], v[206:209], v[46:49]
	v_mfma_f32_16x16x32_bf16 v[30:33], v[146:149], v[214:217], v[30:33]
	v_mfma_f32_16x16x32_bf16 v[30:33], v[150:153], v[218:221], v[30:33]
	v_mfma_f32_16x16x32_bf16 v[22:25], v[164:167], v[218:221], v[22:25]
	v_mfma_f32_16x16x32_bf16 v[22:25], v[160:163], v[214:217], v[22:25]
	v_mfma_f32_16x16x32_bf16 v[6:9], v[160:163], v[222:225], v[6:9]
	v_mfma_f32_16x16x32_bf16 v[6:9], v[164:167], v[226:229], v[6:9]
	v_mfma_f32_16x16x32_bf16 v[14:17], v[150:153], v[226:229], v[14:17]
	v_mfma_f32_16x16x32_bf16 v[14:17], v[146:149], v[222:225], v[14:17]
	v_mfma_f32_16x16x32_bf16 v[58:61], v[168:171], v[184:187], v[58:61]
	v_mfma_f32_16x16x32_bf16 v[58:61], v[172:175], v[188:191], v[58:61]
	v_mfma_f32_16x16x32_bf16 v[50:53], v[180:183], v[188:191], v[50:53]
	v_mfma_f32_16x16x32_bf16 v[50:53], v[176:179], v[184:187], v[50:53]
	v_mfma_f32_16x16x32_bf16 v[34:37], v[176:179], v[206:209], v[34:37]
	v_mfma_f32_16x16x32_bf16 v[34:37], v[180:183], v[210:213], v[34:37]
	v_mfma_f32_16x16x32_bf16 v[42:45], v[172:175], v[210:213], v[42:45]
	v_mfma_f32_16x16x32_bf16 v[42:45], v[168:171], v[206:209], v[42:45]
	v_mfma_f32_16x16x32_bf16 v[26:29], v[168:171], v[214:217], v[26:29]
	v_mfma_f32_16x16x32_bf16 v[26:29], v[172:175], v[218:221], v[26:29]
	v_mfma_f32_16x16x32_bf16 v[18:21], v[180:183], v[218:221], v[18:21]
	v_mfma_f32_16x16x32_bf16 v[18:21], v[176:179], v[214:217], v[18:21]
	v_mfma_f32_16x16x32_bf16 v[2:5], v[176:179], v[222:225], v[2:5]
	v_mfma_f32_16x16x32_bf16 v[2:5], v[180:183], v[226:229], v[2:5]
	v_mfma_f32_16x16x32_bf16 v[10:13], v[172:175], v[226:229], v[10:13]
	v_mfma_f32_16x16x32_bf16 v[10:13], v[168:171], v[222:225], v[10:13]
	s_barrier
	s_add_i32 s57, s57, 2
	s_add_u32 s55, s55, 0x100
	s_addc_u32 s56, s56, 0
	s_cmp_gt_u32 s57, 13
	s_mov_b64 s[22:23], s[24:25]
	s_cbranch_scc1 .Lpeel_exit_2
